# DA: the 18 bias-table LDS lookups of a unit issued in two bursts of 9 with counted lgkmcnt waits (was read/wait/add x18)
# speedup vs baseline: 1.0054x; 1.0054x over previous
; #define LAS __attribute__((address_space(3)))
; DI void phase_da(const Ctx& c, LAS unsigned char* lds, int g, const bf16* PROJ, bf16* DAO, float* DALSE, int bid, int nb, int tid) {
;     ...
;         { const LAS float* tl = tab + 16 + gq * 4 - li;
; #pragma unroll
;         for (int tt = 0; tt < 9; ++tt)
; #pragma unroll
;             for (int j = 0; j < 4; ++j) sc[tt][j] += tl[tt * 16 + j]; }
;         if (cu0 == 0 || cu0 + 128 == cL) {
.LBB0_253:
	s_add_i32 s8, s45, 0x12040
	v_lshlrev_b32_e32 v1, 2, v86
	v_add3_u32 v1, s8, v1, v137
	ds_read2_b32 v[164:165], v1 offset1:1
	ds_read2_b32 v[166:167], v1 offset0:2 offset1:3
	ds_read2_b32 v[168:169], v1 offset0:16 offset1:17
	ds_read2_b32 v[170:171], v1 offset0:18 offset1:19
	ds_read2_b32 v[172:173], v1 offset0:32 offset1:33
	ds_read2_b32 v[174:175], v1 offset0:34 offset1:35
	ds_read2_b32 v[176:177], v1 offset0:48 offset1:49
	ds_read2_b32 v[178:179], v1 offset0:50 offset1:51
	ds_read2_b32 v[180:181], v1 offset0:64 offset1:65
	s_cmp_eq_u32 s33, 0
	s_cselect_b64 s[8:9], -1, 0
	s_add_i32 s37, s33, 0x80
	s_cmp_eq_u32 s37, s46
	s_cselect_b64 s[48:49], -1, 0
	s_or_b64 s[8:9], s[8:9], s[48:49]
	s_andn2_b64 vcc, exec, s[8:9]
	s_waitcnt lgkmcnt(8)
	v_pk_add_f32 v[94:95], v[62:63], v[164:165]
	s_waitcnt lgkmcnt(7)
	v_pk_add_f32 v[92:93], v[64:65], v[166:167]
	s_waitcnt lgkmcnt(6)
	v_pk_add_f32 v[90:91], v[78:79], v[168:169]
	s_waitcnt lgkmcnt(5)
	v_pk_add_f32 v[78:79], v[80:81], v[170:171]
	s_waitcnt lgkmcnt(4)
	v_pk_add_f32 v[80:81], v[74:75], v[172:173]
	s_waitcnt lgkmcnt(3)
	v_pk_add_f32 v[76:77], v[76:77], v[174:175]
	s_waitcnt lgkmcnt(2)
	v_pk_add_f32 v[74:75], v[70:71], v[176:177]
	s_waitcnt lgkmcnt(1)
	v_pk_add_f32 v[70:71], v[72:73], v[178:179]
	s_waitcnt lgkmcnt(0)
	v_pk_add_f32 v[66:67], v[66:67], v[180:181]
	ds_read2_b32 v[182:183], v1 offset0:66 offset1:67
	ds_read2_b32 v[184:185], v1 offset0:80 offset1:81
	ds_read2_b32 v[186:187], v1 offset0:82 offset1:83
	ds_read2_b32 v[188:189], v1 offset0:96 offset1:97
	ds_read2_b32 v[190:191], v1 offset0:98 offset1:99
	ds_read2_b32 v[192:193], v1 offset0:112 offset1:113
	ds_read2_b32 v[194:195], v1 offset0:114 offset1:115
	ds_read2_b32 v[196:197], v1 offset0:128 offset1:129
	ds_read2_b32 v[198:199], v1 offset0:130 offset1:131
	s_waitcnt lgkmcnt(8)
	v_pk_add_f32 v[62:63], v[68:69], v[182:183]
	s_waitcnt lgkmcnt(7)
	v_pk_add_f32 v[64:65], v[58:59], v[184:185]
	s_waitcnt lgkmcnt(6)
	v_pk_add_f32 v[60:61], v[60:61], v[186:187]
	s_waitcnt lgkmcnt(5)
	v_pk_add_f32 v[68:69], v[50:51], v[188:189]
	s_waitcnt lgkmcnt(4)
	v_pk_add_f32 v[58:59], v[52:53], v[190:191]
	s_waitcnt lgkmcnt(3)
	v_pk_add_f32 v[52:53], v[54:55], v[192:193]
	s_waitcnt lgkmcnt(2)
	v_pk_add_f32 v[50:51], v[56:57], v[194:195]
	s_waitcnt lgkmcnt(1)
	v_pk_add_f32 v[46:47], v[46:47], v[196:197]
	s_waitcnt lgkmcnt(0)
	v_pk_add_f32 v[2:3], v[48:49], v[198:199]
	s_cbranch_vccnz .LBB0_255
; DI void phase_da(const Ctx& c, LAS unsigned char* lds, int g, const bf16* PROJ, bf16* DAO, float* DALSE, int bid, int nb, int tid) {
;     ...
;         if (cu0 == 0 || cu0 + 128 == cL) {
; #pragma unroll
;             for (int tt = 0; tt < 9; ++tt)
; #pragma unroll
;                 for (int j = 0; j < 4; ++j) { const int ukj = cu0 - 64 + (w + tt) * 16 + gq * 4 + j; sc[tt][j] = (ukj >= 0 && ukj < cL) ? sc[tt][j] : -1e30f; } }
	v_add_u32_e32 v1, s33, v99
	v_add_u32_e32 v48, v1, v97
	v_cmp_lt_i32_e32 vcc, -1, v48
	v_cmp_gt_i32_e64 s[8:9], s46, v48
	s_and_b64 vcc, vcc, s[8:9]
	v_add_u32_e32 v49, 1, v48
	v_cndmask_b32_e32 v94, v217, v94, vcc
	v_cmp_lt_i32_e32 vcc, -2, v48
	v_cmp_gt_i32_e64 s[8:9], s46, v49
	s_and_b64 vcc, vcc, s[8:9]
	v_add_u32_e32 v49, 2, v48
	v_cndmask_b32_e32 v95, v217, v95, vcc
	v_cmp_lt_i32_e32 vcc, -3, v48
	v_cmp_gt_i32_e64 s[8:9], s46, v49
	s_and_b64 vcc, vcc, s[8:9]
	v_add_u32_e32 v49, 3, v48
	v_cndmask_b32_e32 v92, v217, v92, vcc
	v_cmp_lt_i32_e32 vcc, -4, v48
	v_cmp_gt_i32_e64 s[8:9], s46, v49
	s_and_b64 vcc, vcc, s[8:9]
	v_add_u32_e32 v48, v1, v104
	v_cndmask_b32_e32 v93, v217, v93, vcc
	v_cmp_lt_i32_e32 vcc, -1, v48
	v_cmp_gt_i32_e64 s[8:9], s46, v48
	s_and_b64 vcc, vcc, s[8:9]
	v_add_u32_e32 v49, 1, v48
	v_cndmask_b32_e32 v90, v217, v90, vcc
	v_cmp_lt_i32_e32 vcc, -2, v48
	v_cmp_gt_i32_e64 s[8:9], s46, v49
	s_and_b64 vcc, vcc, s[8:9]
	v_add_u32_e32 v49, 2, v48
	v_cndmask_b32_e32 v91, v217, v91, vcc
	v_cmp_lt_i32_e32 vcc, -3, v48
	v_cmp_gt_i32_e64 s[8:9], s46, v49
	s_and_b64 vcc, vcc, s[8:9]
	v_add_u32_e32 v49, 3, v48
	v_cndmask_b32_e32 v78, v217, v78, vcc
	v_cmp_lt_i32_e32 vcc, -4, v48
	v_cmp_gt_i32_e64 s[8:9], s46, v49
	s_and_b64 vcc, vcc, s[8:9]
	v_add_u32_e32 v48, v1, v106
	v_cndmask_b32_e32 v79, v217, v79, vcc
	v_cmp_lt_i32_e32 vcc, -1, v48
	v_cmp_gt_i32_e64 s[8:9], s46, v48
	s_and_b64 vcc, vcc, s[8:9]
	v_add_u32_e32 v49, 1, v48
	v_cndmask_b32_e32 v80, v217, v80, vcc
	v_cmp_lt_i32_e32 vcc, -2, v48
	v_cmp_gt_i32_e64 s[8:9], s46, v49
	s_and_b64 vcc, vcc, s[8:9]
	v_add_u32_e32 v49, 2, v48
	v_cndmask_b32_e32 v81, v217, v81, vcc
	v_cmp_lt_i32_e32 vcc, -3, v48
	v_cmp_gt_i32_e64 s[8:9], s46, v49
	s_and_b64 vcc, vcc, s[8:9]
	v_add_u32_e32 v49, 3, v48
	v_cndmask_b32_e32 v76, v217, v76, vcc
	v_cmp_lt_i32_e32 vcc, -4, v48
	v_cmp_gt_i32_e64 s[8:9], s46, v49
	s_and_b64 vcc, vcc, s[8:9]
	v_add_u32_e32 v48, v1, v108
	v_cndmask_b32_e32 v77, v217, v77, vcc
	v_cmp_lt_i32_e32 vcc, -1, v48
	v_cmp_gt_i32_e64 s[8:9], s46, v48
	s_and_b64 vcc, vcc, s[8:9]
	v_add_u32_e32 v49, 1, v48
	v_cndmask_b32_e32 v74, v217, v74, vcc
	v_cmp_lt_i32_e32 vcc, -2, v48
	v_cmp_gt_i32_e64 s[8:9], s46, v49
	s_and_b64 vcc, vcc, s[8:9]
	v_add_u32_e32 v49, 2, v48
	v_cndmask_b32_e32 v75, v217, v75, vcc
	v_cmp_lt_i32_e32 vcc, -3, v48
	v_cmp_gt_i32_e64 s[8:9], s46, v49
	s_and_b64 vcc, vcc, s[8:9]
	v_add_u32_e32 v49, 3, v48
	v_cndmask_b32_e32 v70, v217, v70, vcc
	v_cmp_lt_i32_e32 vcc, -4, v48
	v_cmp_gt_i32_e64 s[8:9], s46, v49
	s_and_b64 vcc, vcc, s[8:9]
	v_add_u32_e32 v48, v1, v110
	v_cndmask_b32_e32 v71, v217, v71, vcc
	v_cmp_lt_i32_e32 vcc, -1, v48
	v_cmp_gt_i32_e64 s[8:9], s46, v48
	s_and_b64 vcc, vcc, s[8:9]
	v_add_u32_e32 v49, 1, v48
	v_cndmask_b32_e32 v66, v217, v66, vcc
	v_cmp_lt_i32_e32 vcc, -2, v48
	v_cmp_gt_i32_e64 s[8:9], s46, v49
	s_and_b64 vcc, vcc, s[8:9]
	v_add_u32_e32 v49, 2, v48
	v_cndmask_b32_e32 v67, v217, v67, vcc
	v_cmp_lt_i32_e32 vcc, -3, v48
	v_cmp_gt_i32_e64 s[8:9], s46, v49
	s_and_b64 vcc, vcc, s[8:9]
	v_add_u32_e32 v49, 3, v48
	v_cndmask_b32_e32 v62, v217, v62, vcc
	v_cmp_lt_i32_e32 vcc, -4, v48
	v_cmp_gt_i32_e64 s[8:9], s46, v49
	s_and_b64 vcc, vcc, s[8:9]
	v_add_u32_e32 v48, v1, v112
	v_cndmask_b32_e32 v63, v217, v63, vcc
	v_cmp_lt_i32_e32 vcc, -1, v48
	v_cmp_gt_i32_e64 s[8:9], s46, v48
	s_and_b64 vcc, vcc, s[8:9]
	v_add_u32_e32 v49, 1, v48
	v_cndmask_b32_e32 v64, v217, v64, vcc
	v_cmp_lt_i32_e32 vcc, -2, v48
	v_cmp_gt_i32_e64 s[8:9], s46, v49
	s_and_b64 vcc, vcc, s[8:9]
	v_add_u32_e32 v49, 2, v48
	v_cndmask_b32_e32 v65, v217, v65, vcc
	v_cmp_lt_i32_e32 vcc, -3, v48
	v_cmp_gt_i32_e64 s[8:9], s46, v49
	s_and_b64 vcc, vcc, s[8:9]
	v_add_u32_e32 v49, 3, v48
	v_cndmask_b32_e32 v60, v217, v60, vcc
	v_cmp_lt_i32_e32 vcc, -4, v48
	v_cmp_gt_i32_e64 s[8:9], s46, v49
	s_and_b64 vcc, vcc, s[8:9]
	v_add_u32_e32 v48, v1, v114
	v_cndmask_b32_e32 v61, v217, v61, vcc
	v_cmp_lt_i32_e32 vcc, -1, v48
	v_cmp_gt_i32_e64 s[8:9], s46, v48
	s_and_b64 vcc, vcc, s[8:9]
	v_add_u32_e32 v49, 1, v48
	v_cndmask_b32_e32 v68, v217, v68, vcc
	v_cmp_lt_i32_e32 vcc, -2, v48
	v_cmp_gt_i32_e64 s[8:9], s46, v49
	s_and_b64 vcc, vcc, s[8:9]
	v_add_u32_e32 v49, 2, v48
	v_cndmask_b32_e32 v69, v217, v69, vcc
	v_cmp_lt_i32_e32 vcc, -3, v48
	v_cmp_gt_i32_e64 s[8:9], s46, v49
	s_and_b64 vcc, vcc, s[8:9]
	v_add_u32_e32 v49, 3, v48
	v_cndmask_b32_e32 v58, v217, v58, vcc
	v_cmp_lt_i32_e32 vcc, -4, v48
	v_cmp_gt_i32_e64 s[8:9], s46, v49
	s_and_b64 vcc, vcc, s[8:9]
	v_add_u32_e32 v48, v1, v116
	v_cndmask_b32_e32 v59, v217, v59, vcc
	v_cmp_lt_i32_e32 vcc, -1, v48
	v_cmp_gt_i32_e64 s[8:9], s46, v48
	s_and_b64 vcc, vcc, s[8:9]
	v_add_u32_e32 v49, 1, v48
	v_cndmask_b32_e32 v52, v217, v52, vcc
	v_cmp_lt_i32_e32 vcc, -2, v48
	v_cmp_gt_i32_e64 s[8:9], s46, v49
	s_and_b64 vcc, vcc, s[8:9]
	v_add_u32_e32 v49, 2, v48
	v_cndmask_b32_e32 v53, v217, v53, vcc
	v_cmp_lt_i32_e32 vcc, -3, v48
	v_cmp_gt_i32_e64 s[8:9], s46, v49
	s_and_b64 vcc, vcc, s[8:9]
	v_add_u32_e32 v49, 3, v48
	v_cndmask_b32_e32 v50, v217, v50, vcc
	v_cmp_lt_i32_e32 vcc, -4, v48
	v_cmp_gt_i32_e64 s[8:9], s46, v49
	s_and_b64 vcc, vcc, s[8:9]
	v_add_u32_e32 v1, v1, v118
	v_cndmask_b32_e32 v51, v217, v51, vcc
	v_cmp_lt_i32_e32 vcc, -1, v1
	v_cmp_gt_i32_e64 s[8:9], s46, v1
	s_and_b64 vcc, vcc, s[8:9]
	v_add_u32_e32 v48, 1, v1
	v_cndmask_b32_e32 v46, v217, v46, vcc
	v_cmp_lt_i32_e32 vcc, -2, v1
	v_cmp_gt_i32_e64 s[8:9], s46, v48
	s_and_b64 vcc, vcc, s[8:9]
	v_add_u32_e32 v48, 2, v1
	v_cndmask_b32_e32 v47, v217, v47, vcc
	v_cmp_lt_i32_e32 vcc, -3, v1
	v_cmp_gt_i32_e64 s[8:9], s46, v48
	s_and_b64 vcc, vcc, s[8:9]
	v_add_u32_e32 v48, 3, v1
	v_cndmask_b32_e32 v2, v217, v2, vcc
	v_cmp_lt_i32_e32 vcc, -4, v1
	v_cmp_gt_i32_e64 s[8:9], s46, v48
	s_and_b64 vcc, vcc, s[8:9]
	v_cndmask_b32_e32 v3, v217, v3, vcc
